# phase 6 sample recurrence: all four tokens' g/beta/v scalars loaded up front (no dependent loads in the token loop)
# baseline (speedup 1.0000x reference)
; __device__ __forceinline__ float bf2f(unsigned short x) { return __uint_as_float(((unsigned)x) << 16); }
; __device__ __forceinline__ void scan_phase(const Params& p, int bid, int nblk, LAS unsigned char* lds) {
;     ...
;         for (int it0 = bid * 2; it0 < 1024; it0 += nblk * 2) {
;             const int item = it0 + grp, sb = item >> 3, h = item & 7;
;             __syncthreads();
; #pragma unroll
;             for (int i = 0; i < 4; ++i) { const int idx = (tid & 255) + 256 * i, tk = idx >> 7, c = idx & 127, t = tk & 3; const size_t go = (size_t)(TP + sb * 4 + t) * 1024 + h * 128 + c;
;                 if (tk < 4) qs[t * 128 + c] = bf2f(qn[go]); else ks[t * 128 + c] = bf2f(kn[go]); }
;             float S[64];
;             const float* s0 = p.in[4] + (size_t)item * 16384 + (size_t)half * 64 * 128 + j;
; #pragma unroll
;             for (int i = 0; i < 64; ++i) S[i] = __builtin_nontemporal_load(s0 + i * 128);
;             __syncthreads();
; #pragma unroll 1
;             for (int t = 0; t < 4; ++t) {
;                 const int row = TP + sb * 4 + t;
;                 const float a = __expf(gbuf[row * 8 + h]), be = bbuf[row * 8 + h], v = bf2f(vv[(size_t)row * 1024 + h * 128 + j]);
.LBB0_1099:
	v_add_u32_e32 v0, s3, v143
	v_ashrrev_i32_e32 v16, 1, v0
	v_and_b32_e32 v2, -4, v16
	v_add_u32_e32 v3, 0x2000, v2
	v_or_b32_e32 v4, v3, v145
	v_ashrrev_i32_e32 v5, 31, v4
	v_or_b32_e32 v8, v3, v147
	v_or_b32_e32 v10, v3, v148
	v_and_b32_e32 v1, 7, v0
	v_lshlrev_b64 v[4:5], 11, v[4:5]
	v_ashrrev_i32_e32 v9, 31, v8
	v_ashrrev_i32_e32 v11, 31, v10
	v_lshl_add_u64 v[6:7], s[8:9], 0, v[4:5]
	v_lshl_or_b32 v64, v1, 8, v152
	v_lshlrev_b64 v[8:9], 11, v[8:9]
	v_lshl_add_u64 v[4:5], s[10:11], 0, v[4:5]
	v_lshlrev_b64 v[10:11], 11, v[10:11]
	v_lshl_add_u64 v[6:7], v[6:7], 0, v[64:65]
	v_lshl_add_u64 v[8:9], s[8:9], 0, v[8:9]
	v_lshl_add_u64 v[4:5], v[4:5], 0, v[64:65]
	v_lshl_add_u64 v[10:11], s[10:11], 0, v[10:11]
	v_ashrrev_i32_e32 v1, 31, v0
	s_barrier
	v_lshl_add_u64 v[8:9], v[8:9], 0, v[64:65]
	v_lshl_add_u64 v[10:11], v[10:11], 0, v[64:65]
	global_load_ushort v3, v[6:7], off
	global_load_ushort v17, v[8:9], off
	global_load_ushort v18, v[4:5], off
	global_load_ushort v19, v[10:11], off
	v_lshlrev_b64 v[4:5], 16, v[0:1]
	v_lshl_add_u64 v[4:5], v[66:67], 0, v[4:5]
	v_add_co_u32_e32 v6, vcc, s28, v4
	global_load_dword v76, v[4:5], off nt
	global_load_dword v77, v[4:5], off offset:512 nt
	global_load_dword v74, v[4:5], off offset:1024 nt
	global_load_dword v75, v[4:5], off offset:1536 nt
	global_load_dword v72, v[4:5], off offset:2048 nt
	global_load_dword v73, v[4:5], off offset:2560 nt
	global_load_dword v70, v[4:5], off offset:3072 nt
	global_load_dword v71, v[4:5], off offset:3584 nt
	v_addc_co_u32_e32 v7, vcc, 0, v5, vcc
	v_add_co_u32_e32 v8, vcc, s27, v4
	v_lshlrev_b64 v[134:135], 14, v[0:1]
	s_nop 0
	v_addc_co_u32_e32 v9, vcc, 0, v5, vcc
	v_add_co_u32_e32 v10, vcc, s29, v4
	s_mov_b32 s37, 0
	s_nop 0
	v_addc_co_u32_e32 v11, vcc, 0, v5, vcc
	v_add_co_u32_e32 v12, vcc, s30, v4
	s_waitcnt vmcnt(11)
	v_lshlrev_b32_e32 v3, 16, v3
	v_addc_co_u32_e32 v13, vcc, 0, v5, vcc
	global_load_dword v103, v[6:7], off offset:512 nt
	global_load_dword v100, v[6:7], off offset:1024 nt
	global_load_dword v101, v[6:7], off offset:1536 nt
	global_load_dword v98, v[6:7], off offset:2048 nt
	global_load_dword v99, v[6:7], off offset:2560 nt
	global_load_dword v96, v[6:7], off offset:3072 nt
	global_load_dword v97, v[6:7], off offset:3584 nt
	global_load_dword v81, v[10:11], off offset:512 nt
	global_load_dword v86, v[8:9], off offset:1024 nt
	global_load_dword v87, v[8:9], off offset:1536 nt
	global_load_dword v84, v[8:9], off offset:2048 nt
	global_load_dword v85, v[8:9], off offset:2560 nt
	global_load_dword v82, v[8:9], off offset:3072 nt
	global_load_dword v83, v[8:9], off offset:3584 nt
	global_load_dword v80, v[12:13], off offset:-4096 nt
	global_load_dword v78, v[12:13], off nt
	v_add_co_u32_e32 v6, vcc, s31, v4
	s_nop 1
	v_addc_co_u32_e32 v7, vcc, 0, v5, vcc
	v_add_co_u32_e32 v14, vcc, s34, v4
	s_nop 1
	v_addc_co_u32_e32 v15, vcc, 0, v5, vcc
	global_load_dword v79, v[12:13], off offset:512 nt
	global_load_dword v92, v[12:13], off offset:1024 nt
	global_load_dword v93, v[12:13], off offset:1536 nt
	global_load_dword v90, v[12:13], off offset:2048 nt
	global_load_dword v91, v[12:13], off offset:2560 nt
	global_load_dword v88, v[12:13], off offset:3072 nt
	global_load_dword v89, v[12:13], off offset:3584 nt
	global_load_dword v94, v[14:15], off offset:-4096 nt
	global_load_dword v126, v[10:11], off offset:1024 nt
	global_load_dword v127, v[10:11], off offset:1536 nt
	global_load_dword v124, v[10:11], off offset:2048 nt
	global_load_dword v125, v[10:11], off offset:2560 nt
	global_load_dword v122, v[10:11], off offset:3072 nt
	global_load_dword v123, v[10:11], off offset:3584 nt
	global_load_dword v95, v[6:7], off offset:512 nt
	global_load_dword v116, v[6:7], off offset:1024 nt
	global_load_dword v110, v[14:15], off nt
	global_load_dword v111, v[14:15], off offset:512 nt
	global_load_dword v108, v[14:15], off offset:1024 nt
	global_load_dword v109, v[14:15], off offset:1536 nt
	global_load_dword v106, v[14:15], off offset:2048 nt
	global_load_dword v107, v[14:15], off offset:2560 nt
	global_load_dword v104, v[14:15], off offset:3072 nt
	global_load_dword v105, v[14:15], off offset:3584 nt
	v_add_co_u32_e32 v4, vcc, s35, v4
	s_nop 1
	v_addc_co_u32_e32 v5, vcc, 0, v5, vcc
	global_load_dword v117, v[6:7], off offset:1536 nt
	global_load_dword v130, v[6:7], off offset:2048 nt
	global_load_dword v131, v[6:7], off offset:2560 nt
	global_load_dword v128, v[6:7], off offset:3072 nt
	global_load_dword v129, v[6:7], off offset:3584 nt
	global_load_dword v114, v[4:5], off nt
	global_load_dword v115, v[4:5], off offset:512 nt
	global_load_dword v112, v[4:5], off offset:1024 nt
	global_load_dword v102, v[8:9], off offset:-4096 nt
	global_load_dword v132, v[8:9], off nt
	global_load_dword v133, v[8:9], off offset:512 nt
	global_load_dword v113, v[4:5], off offset:1536 nt
	global_load_dword v120, v[4:5], off offset:2048 nt
	global_load_dword v121, v[4:5], off offset:2560 nt
	global_load_dword v118, v[4:5], off offset:3072 nt
	global_load_dword v119, v[4:5], off offset:3584 nt
	s_waitcnt vmcnt(62)
	v_lshlrev_b32_e32 v6, 16, v17
	ds_write2st64_b32 v146, v3, v6 offset1:4
	v_lshlrev_b32_e32 v3, 16, v18
	ds_write_b32 v146, v3 offset:2048
	v_lshlrev_b32_e32 v3, 16, v19
	v_and_b32_e32 v4, 7, v151
	ds_write_b32 v153, v3 offset:2048
	v_ashrrev_i32_e32 v3, 31, v2
	v_lshl_or_b32 v5, v4, 7, v149
	v_lshlrev_b64 v[0:1], 11, v[2:3]
	v_lshl_or_b32 v0, v5, 1, v0
	v_lshl_add_u64 v[136:137], s[14:15], 0, v[0:1]
	v_lshlrev_b64 v[0:1], 12, v[2:3]
	v_lshl_or_b32 v0, v5, 2, v0
	v_lshl_add_u64 v[138:139], s[12:13], 0, v[0:1]
	v_lshlrev_b32_e32 v0, 3, v16
	v_and_or_b32 v0, v0, s36, v4
	v_add_u32_e32 v140, 0x10000, v0
	v_lshlrev_b32_e32 v186, 2, v140
	v_lshl_add_u64 v[188:189], v[136:137], 0, s[22:23]
	global_load_dword v190, v186, s[16:17]
	global_load_dword v191, v186, s[16:17] offset:32
	global_load_dword v192, v186, s[16:17] offset:64
	global_load_dword v193, v186, s[16:17] offset:96
	global_load_dword v194, v186, s[18:19]
	global_load_dword v195, v186, s[18:19] offset:32
	global_load_dword v196, v186, s[18:19] offset:64
	global_load_dword v197, v186, s[18:19] offset:96
	global_load_ushort v198, v[136:137], off
	global_load_ushort v199, v[136:137], off offset:2048
	global_load_ushort v200, v[188:189], off
	global_load_ushort v201, v[188:189], off offset:2048
	s_waitcnt vmcnt(0)
	s_waitcnt lgkmcnt(0)
	s_barrier
	s_branch .LBB0_1101

; #define LAS __attribute__((address_space(3)))
; __device__ __forceinline__ float bf2f(unsigned short x) { return __uint_as_float(((unsigned)x) << 16); }
; __device__ __forceinline__ void scan_phase(const Params& p, int bid, int nblk, LAS unsigned char* lds) {
;     ...
;             for (int t = 0; t < 4; ++t) {
;                 const int row = TP + sb * 4 + t;
;                 const float a = __expf(gbuf[row * 8 + h]), be = bbuf[row * 8 + h], v = bf2f(vv[(size_t)row * 1024 + h * 128 + j]);
;                 float kS = 0.f;
; #pragma unroll
;                 for (int i4 = 0; i4 < 16; ++i4) { const f32x4 k4 = *(const LAS f32x4*)(ks + t * 128 + half * 64 + i4 * 4); kS += k4[0] * S[i4 * 4] + k4[1] * S[i4 * 4 + 1] + k4[2] * S[i4 * 4 + 2] + k4[3] * S[i4 * 4 + 3]; }
;                 kS += __shfl_xor(kS, 32);
;                 const float coef = be * (v - a * kS);
.LBB0_1101:
	v_ashrrev_i32_e32 v141, 31, v140
	s_waitcnt lgkmcnt(0)
	v_lshlrev_b64 v[0:1], 2, v[140:141]
	v_lshl_add_u64 v[2:3], s[16:17], 0, v[0:1]
	v_add_u32_e32 v141, s37, v144
	v_lshl_add_u64 v[0:1], s[18:19], 0, v[0:1]
	ds_read_b128 v[60:63], v141 offset:2048
	v_mov_b32_e32 v64, v190
	v_mov_b32_e32 v142, v194
	v_mov_b32_e32 v161, v198
	v_mov_b32_e32 v190, v191
	v_mov_b32_e32 v191, v192
	v_mov_b32_e32 v192, v193
	v_mov_b32_e32 v194, v195
	v_mov_b32_e32 v195, v196
	v_mov_b32_e32 v196, v197
	v_mov_b32_e32 v198, v199
	v_mov_b32_e32 v199, v200
	v_mov_b32_e32 v200, v201
	ds_read_b128 v[56:59], v141 offset:2064
	ds_read_b128 v[52:55], v141 offset:2080
	ds_read_b128 v[48:51], v141 offset:2096
	ds_read_b128 v[44:47], v141 offset:2112
	s_waitcnt lgkmcnt(4)
	v_mul_f32_e32 v0, v77, v61
	v_fmac_f32_e32 v0, v76, v60
	s_waitcnt lgkmcnt(3)
	v_mul_f32_e32 v1, v73, v57
	v_fmac_f32_e32 v0, v74, v62
	v_fmac_f32_e32 v1, v72, v56
	v_fmac_f32_e32 v0, v75, v63
	v_fmac_f32_e32 v1, v70, v58
	v_add_f32_e32 v0, 0, v0
	v_fmac_f32_e32 v1, v71, v59
	v_add_f32_e32 v0, v0, v1
	s_waitcnt lgkmcnt(2)
	v_mul_f32_e32 v1, v103, v53
	v_fmac_f32_e32 v1, v102, v52
	v_fmac_f32_e32 v1, v100, v54
	v_fmac_f32_e32 v1, v101, v55
	v_add_f32_e32 v0, v0, v1
	s_waitcnt lgkmcnt(1)
	v_mul_f32_e32 v1, v99, v49
	v_fmac_f32_e32 v1, v98, v48
	v_fmac_f32_e32 v1, v96, v50
	v_fmac_f32_e32 v1, v97, v51
	ds_read_b128 v[40:43], v141 offset:2128
	ds_read_b128 v[36:39], v141 offset:2144
	v_add_f32_e32 v0, v0, v1
	s_waitcnt lgkmcnt(2)
	v_mul_f32_e32 v1, v133, v45
	v_fmac_f32_e32 v1, v132, v44
	v_fmac_f32_e32 v1, v86, v46
	v_fmac_f32_e32 v1, v87, v47
	v_add_f32_e32 v0, v0, v1
	s_waitcnt lgkmcnt(1)
	v_mul_f32_e32 v1, v85, v41
	v_fmac_f32_e32 v1, v84, v40
	v_fmac_f32_e32 v1, v82, v42
	v_fmac_f32_e32 v1, v83, v43
	ds_read_b128 v[32:35], v141 offset:2160
	v_add_f32_e32 v0, v0, v1
	s_waitcnt lgkmcnt(1)
	v_mul_f32_e32 v1, v81, v37
	v_fmac_f32_e32 v1, v80, v36
	v_fmac_f32_e32 v1, v126, v38
	ds_read_b128 v[28:31], v141 offset:2176
	ds_read_b128 v[20:23], v141 offset:2192
	v_fmac_f32_e32 v1, v127, v39
	v_add_f32_e32 v0, v0, v1
	s_waitcnt lgkmcnt(2)
	v_mul_f32_e32 v1, v125, v33
	v_fmac_f32_e32 v1, v124, v32
	v_fmac_f32_e32 v1, v122, v34
	v_fmac_f32_e32 v1, v123, v35
	v_mov_b32_e32 v4, v79
	v_mov_b32_e32 v5, v91
	s_waitcnt lgkmcnt(1)
	v_mov_b32_e32 v6, v29
	s_waitcnt lgkmcnt(0)
	v_mov_b32_e32 v7, v21
	ds_read_b128 v[24:27], v141 offset:2208
	ds_read_b128 v[12:15], v141 offset:2224
	v_add_f32_e32 v8, v0, v1
	v_mov_b32_e32 v0, v78
	v_mov_b32_e32 v1, v90
	v_mov_b32_e32 v2, v28
	v_mov_b32_e32 v3, v20
	v_pk_mul_f32 v[4:5], v[4:5], v[6:7]
	s_waitcnt lgkmcnt(1)
	v_mov_b32_e32 v6, v25
	v_pk_fma_f32 v[0:1], v[0:1], v[2:3], v[4:5]
	v_mov_b32_e32 v2, v92
	v_mov_b32_e32 v3, v88
	v_mov_b32_e32 v4, v30
	v_mov_b32_e32 v5, v22
	v_pk_fma_f32 v[0:1], v[2:3], v[4:5], v[0:1]
	v_mov_b32_e32 v2, v93
	v_mov_b32_e32 v3, v89
	v_mov_b32_e32 v4, v31
	v_mov_b32_e32 v5, v23
	v_pk_fma_f32 v[0:1], v[2:3], v[4:5], v[0:1]
	v_mov_b32_e32 v4, v95
	v_add_f32_e32 v0, v8, v0
	v_mov_b32_e32 v5, v131
	s_waitcnt lgkmcnt(0)
	v_mov_b32_e32 v7, v13
	v_add_f32_e32 v8, v0, v1
	v_mov_b32_e32 v0, v94
	v_mov_b32_e32 v1, v130
	v_mov_b32_e32 v2, v24
	v_mov_b32_e32 v3, v12
	v_pk_mul_f32 v[4:5], v[4:5], v[6:7]
	v_mov_b32_e32 v9, v107
	v_pk_fma_f32 v[0:1], v[0:1], v[2:3], v[4:5]
	v_mov_b32_e32 v2, v116
	v_mov_b32_e32 v3, v128
	v_mov_b32_e32 v4, v26
	v_mov_b32_e32 v5, v14
	v_pk_fma_f32 v[0:1], v[2:3], v[4:5], v[0:1]
	v_mov_b32_e32 v2, v117
	v_mov_b32_e32 v3, v129
	v_mov_b32_e32 v4, v27
	v_mov_b32_e32 v5, v15
	v_pk_fma_f32 v[0:1], v[2:3], v[4:5], v[0:1]
	ds_read_b128 v[16:19], v141 offset:2240
	ds_read_b128 v[4:7], v141 offset:2256
	v_add_f32_e32 v0, v8, v0
	v_mov_b32_e32 v8, v111
	v_add_f32_e32 v156, v0, v1
	s_waitcnt lgkmcnt(1)
	v_mov_b32_e32 v10, v17
	s_waitcnt lgkmcnt(0)
	v_mov_b32_e32 v11, v5
	v_mov_b32_e32 v0, v110
	v_mov_b32_e32 v1, v106
	v_mov_b32_e32 v2, v16
	v_mov_b32_e32 v3, v4
	v_pk_mul_f32 v[8:9], v[8:9], v[10:11]
	v_mov_b32_e32 v158, v115
	v_pk_fma_f32 v[0:1], v[0:1], v[2:3], v[8:9]
	v_mov_b32_e32 v2, v108
	v_mov_b32_e32 v3, v104
	v_mov_b32_e32 v8, v18
	v_mov_b32_e32 v9, v6
	v_pk_fma_f32 v[0:1], v[2:3], v[8:9], v[0:1]
	v_mov_b32_e32 v2, v109
	v_mov_b32_e32 v3, v105
	v_mov_b32_e32 v8, v19
	v_mov_b32_e32 v9, v7
	v_pk_fma_f32 v[154:155], v[2:3], v[8:9], v[0:1]
	ds_read_b128 v[8:11], v141 offset:2272
	ds_read_b128 v[0:3], v141 offset:2288
	v_add_f32_e32 v154, v156, v154
	v_mov_b32_e32 v159, v121
	v_add_f32_e32 v164, v154, v155
	s_waitcnt lgkmcnt(1)
	v_mov_b32_e32 v162, v9
	s_waitcnt lgkmcnt(0)
	v_mov_b32_e32 v163, v1
	v_mov_b32_e32 v154, v114
	v_mov_b32_e32 v155, v120
	v_mov_b32_e32 v156, v8
	v_mov_b32_e32 v157, v0
	v_pk_mul_f32 v[158:159], v[158:159], v[162:163]
	v_mul_f32_e32 v64, 0x3fb8aa3b, v64
	v_pk_fma_f32 v[154:155], v[154:155], v[156:157], v[158:159]
	v_mov_b32_e32 v156, v112
	v_mov_b32_e32 v157, v118
	v_mov_b32_e32 v158, v10
	v_mov_b32_e32 v159, v2
	v_pk_fma_f32 v[154:155], v[156:157], v[158:159], v[154:155]
	v_mov_b32_e32 v156, v113
	v_mov_b32_e32 v157, v119
	v_mov_b32_e32 v158, v11
	v_mov_b32_e32 v159, v3
	v_pk_fma_f32 v[154:155], v[156:157], v[158:159], v[154:155]
	v_exp_f32_e32 v64, v64
	v_add_f32_e32 v154, v164, v154
	v_add_f32_e32 v154, v154, v155
	ds_bpermute_b32 v155, v150, v154
	v_lshlrev_b32_e32 v156, 16, v161
	s_waitcnt lgkmcnt(0)
	v_add_f32_e32 v154, v154, v155
	v_fma_f32 v154, -v64, v154, v156
	v_mul_f32_e32 v142, v142, v154
	ds_read_b128 v[154:157], v141
	ds_read_b128 v[162:165], v141 offset:16
	ds_read_b128 v[168:171], v141 offset:32
	ds_read_b128 v[172:175], v141 offset:48
	v_pk_mul_f32 v[60:61], v[60:61], v[142:143] op_sel_hi:[1,0]
	v_pk_mul_f32 v[62:63], v[62:63], v[142:143] op_sel_hi:[1,0]
	v_pk_fma_f32 v[76:77], v[76:77], v[64:65], v[60:61] op_sel_hi:[1,0,1]
	v_pk_fma_f32 v[74:75], v[74:75], v[64:65], v[62:63] op_sel_hi:[1,0,1]
	s_waitcnt lgkmcnt(3)
; #define LAS __attribute__((address_space(3)))
; __device__ __forceinline__ void scan_phase(const Params& p, int bid, int nblk, LAS unsigned char* lds) {
;     ...
;                 float o = 0.f;
; #pragma unroll
;                 for (int i4 = 0; i4 < 16; ++i4) { const f32x4 k4 = *(const LAS f32x4*)(ks + t * 128 + half * 64 + i4 * 4); const f32x4 q4 = *(const LAS f32x4*)(qs + t * 128 + half * 64 + i4 * 4);
; #pragma unroll
;                     for (int q = 0; q < 4; ++q) { S[i4 * 4 + q] = a * S[i4 * 4 + q] + k4[q] * coef; o += q4[q] * S[i4 * 4 + q]; } }
;                 o += __shfl_xor(o, 32);
;                 if (half == 0) obuf[(size_t)row * 1024 + h * 128 + j] = o * scale;
	v_fma_f32 v60, v154, v76, 0
	v_fmac_f32_e32 v60, v155, v77
	v_fmac_f32_e32 v60, v156, v74
	v_pk_mul_f32 v[56:57], v[56:57], v[142:143] op_sel_hi:[1,0]
	v_fmac_f32_e32 v60, v157, v75
	v_pk_fma_f32 v[72:73], v[72:73], v[64:65], v[56:57] op_sel_hi:[1,0,1]
	v_pk_mul_f32 v[56:57], v[58:59], v[142:143] op_sel_hi:[1,0]
	s_waitcnt lgkmcnt(2)
	v_fmac_f32_e32 v60, v162, v72
	v_fmac_f32_e32 v60, v163, v73
	v_pk_fma_f32 v[70:71], v[70:71], v[64:65], v[56:57] op_sel_hi:[1,0,1]
	v_pk_mul_f32 v[52:53], v[52:53], v[142:143] op_sel_hi:[1,0]
	v_fmac_f32_e32 v60, v164, v70
	v_fmac_f32_e32 v60, v165, v71
	v_pk_fma_f32 v[102:103], v[102:103], v[64:65], v[52:53] op_sel_hi:[1,0,1]
	v_pk_mul_f32 v[52:53], v[54:55], v[142:143] op_sel_hi:[1,0]
	s_waitcnt lgkmcnt(1)
	v_fmac_f32_e32 v60, v168, v102
	v_fmac_f32_e32 v60, v169, v103
	v_pk_fma_f32 v[100:101], v[100:101], v[64:65], v[52:53] op_sel_hi:[1,0,1]
	v_pk_mul_f32 v[48:49], v[48:49], v[142:143] op_sel_hi:[1,0]
	v_fmac_f32_e32 v60, v170, v100
	v_pk_fma_f32 v[98:99], v[98:99], v[64:65], v[48:49] op_sel_hi:[1,0,1]
	v_pk_mul_f32 v[48:49], v[50:51], v[142:143] op_sel_hi:[1,0]
	v_fmac_f32_e32 v60, v171, v101
	v_pk_fma_f32 v[96:97], v[96:97], v[64:65], v[48:49] op_sel_hi:[1,0,1]
	ds_read_b128 v[48:51], v141 offset:64
	ds_read_b128 v[52:55], v141 offset:80
	s_waitcnt lgkmcnt(2)
	v_fmac_f32_e32 v60, v172, v98
	v_fmac_f32_e32 v60, v173, v99
	v_fmac_f32_e32 v60, v174, v96
	v_pk_mul_f32 v[44:45], v[142:143], v[44:45] op_sel_hi:[0,1]
	v_fmac_f32_e32 v60, v175, v97
	v_pk_fma_f32 v[132:133], v[132:133], v[64:65], v[44:45] op_sel_hi:[1,0,1]
	v_pk_mul_f32 v[44:45], v[142:143], v[46:47] op_sel_hi:[0,1]
	s_waitcnt lgkmcnt(1)
	v_fmac_f32_e32 v60, v48, v132
	v_fmac_f32_e32 v60, v49, v133
	v_pk_fma_f32 v[86:87], v[86:87], v[64:65], v[44:45] op_sel_hi:[1,0,1]
	v_pk_mul_f32 v[40:41], v[142:143], v[40:41] op_sel_hi:[0,1]
	v_fmac_f32_e32 v60, v50, v86
	v_pk_fma_f32 v[84:85], v[84:85], v[64:65], v[40:41] op_sel_hi:[1,0,1]
	v_pk_mul_f32 v[40:41], v[142:143], v[42:43] op_sel_hi:[0,1]
	v_fmac_f32_e32 v60, v51, v87
	v_pk_fma_f32 v[82:83], v[82:83], v[64:65], v[40:41] op_sel_hi:[1,0,1]
	ds_read_b128 v[40:43], v141 offset:96
	ds_read_b128 v[44:47], v141 offset:112
	s_waitcnt lgkmcnt(2)
	v_fmac_f32_e32 v60, v52, v84
	v_fmac_f32_e32 v60, v53, v85
	v_fmac_f32_e32 v60, v54, v82
	v_pk_mul_f32 v[36:37], v[142:143], v[36:37] op_sel_hi:[0,1]
	v_fmac_f32_e32 v60, v55, v83
	v_pk_fma_f32 v[80:81], v[80:81], v[64:65], v[36:37] op_sel_hi:[1,0,1]
	v_pk_mul_f32 v[36:37], v[142:143], v[38:39] op_sel_hi:[0,1]
	s_waitcnt lgkmcnt(1)
	v_fmac_f32_e32 v60, v40, v80
	v_fmac_f32_e32 v60, v41, v81
	v_pk_fma_f32 v[126:127], v[126:127], v[64:65], v[36:37] op_sel_hi:[1,0,1]
	v_pk_mul_f32 v[32:33], v[142:143], v[32:33] op_sel_hi:[0,1]
	v_fmac_f32_e32 v60, v42, v126
	v_pk_fma_f32 v[124:125], v[124:125], v[64:65], v[32:33] op_sel_hi:[1,0,1]
	v_pk_mul_f32 v[32:33], v[142:143], v[34:35] op_sel_hi:[0,1]
	v_fmac_f32_e32 v60, v43, v127
	v_pk_fma_f32 v[122:123], v[122:123], v[64:65], v[32:33] op_sel_hi:[1,0,1]
	ds_read_b128 v[32:35], v141 offset:128
	ds_read_b128 v[36:39], v141 offset:144
	s_waitcnt lgkmcnt(2)
	v_fmac_f32_e32 v60, v44, v124
	v_fmac_f32_e32 v60, v45, v125
	v_fmac_f32_e32 v60, v46, v122
	v_pk_mul_f32 v[28:29], v[142:143], v[28:29] op_sel_hi:[0,1]
	v_fmac_f32_e32 v60, v47, v123
	v_pk_fma_f32 v[78:79], v[78:79], v[64:65], v[28:29] op_sel_hi:[1,0,1]
	v_pk_mul_f32 v[28:29], v[142:143], v[30:31] op_sel_hi:[0,1]
	s_waitcnt lgkmcnt(1)
	v_fmac_f32_e32 v60, v32, v78
	v_fmac_f32_e32 v60, v33, v79
	v_pk_fma_f32 v[92:93], v[92:93], v[64:65], v[28:29] op_sel_hi:[1,0,1]
	v_pk_mul_f32 v[20:21], v[142:143], v[20:21] op_sel_hi:[0,1]
	v_fmac_f32_e32 v60, v34, v92
	v_pk_fma_f32 v[90:91], v[90:91], v[64:65], v[20:21] op_sel_hi:[1,0,1]
	v_pk_mul_f32 v[20:21], v[142:143], v[22:23] op_sel_hi:[0,1]
	v_fmac_f32_e32 v60, v35, v93
	v_pk_fma_f32 v[88:89], v[88:89], v[64:65], v[20:21] op_sel_hi:[1,0,1]
	ds_read_b128 v[20:23], v141 offset:160
	ds_read_b128 v[28:31], v141 offset:176
	s_waitcnt lgkmcnt(2)
	v_fmac_f32_e32 v60, v36, v90
	v_fmac_f32_e32 v60, v37, v91
	v_fmac_f32_e32 v60, v38, v88
	v_pk_mul_f32 v[24:25], v[142:143], v[24:25] op_sel_hi:[0,1]
	v_fmac_f32_e32 v60, v39, v89
	v_pk_fma_f32 v[94:95], v[94:95], v[64:65], v[24:25] op_sel_hi:[1,0,1]
	v_pk_mul_f32 v[12:13], v[142:143], v[12:13] op_sel_hi:[0,1]
	s_waitcnt lgkmcnt(1)
	v_fmac_f32_e32 v60, v20, v94
	v_fmac_f32_e32 v60, v21, v95
	v_pk_mul_f32 v[20:21], v[142:143], v[26:27] op_sel_hi:[0,1]
	v_pk_fma_f32 v[116:117], v[116:117], v[64:65], v[20:21] op_sel_hi:[1,0,1]
	v_pk_fma_f32 v[130:131], v[130:131], v[64:65], v[12:13] op_sel_hi:[1,0,1]
	v_fmac_f32_e32 v60, v22, v116
	v_pk_mul_f32 v[12:13], v[142:143], v[14:15] op_sel_hi:[0,1]
	v_fmac_f32_e32 v60, v23, v117
	v_pk_fma_f32 v[128:129], v[128:129], v[64:65], v[12:13] op_sel_hi:[1,0,1]
	ds_read_b128 v[12:15], v141 offset:192
	ds_read_b128 v[20:23], v141 offset:208
	s_waitcnt lgkmcnt(2)
	v_fmac_f32_e32 v60, v28, v130
	v_fmac_f32_e32 v60, v29, v131
	v_fmac_f32_e32 v60, v30, v128
	v_pk_mul_f32 v[16:17], v[142:143], v[16:17] op_sel_hi:[0,1]
	v_fmac_f32_e32 v60, v31, v129
	v_pk_fma_f32 v[110:111], v[110:111], v[64:65], v[16:17] op_sel_hi:[1,0,1]
	v_pk_mul_f32 v[4:5], v[142:143], v[4:5] op_sel_hi:[0,1]
	s_waitcnt lgkmcnt(1)
	v_fmac_f32_e32 v60, v12, v110
	v_fmac_f32_e32 v60, v13, v111
	v_pk_mul_f32 v[12:13], v[142:143], v[18:19] op_sel_hi:[0,1]
	v_pk_fma_f32 v[108:109], v[108:109], v[64:65], v[12:13] op_sel_hi:[1,0,1]
	v_pk_fma_f32 v[106:107], v[106:107], v[64:65], v[4:5] op_sel_hi:[1,0,1]
	v_fmac_f32_e32 v60, v14, v108
	v_pk_mul_f32 v[4:5], v[142:143], v[6:7] op_sel_hi:[0,1]
	v_fmac_f32_e32 v60, v15, v109
	v_pk_fma_f32 v[104:105], v[104:105], v[64:65], v[4:5] op_sel_hi:[1,0,1]
	ds_read_b128 v[4:7], v141 offset:224
	ds_read_b128 v[12:15], v141 offset:240
	s_waitcnt lgkmcnt(2)
	v_fmac_f32_e32 v60, v20, v106
	v_fmac_f32_e32 v60, v21, v107
	v_fmac_f32_e32 v60, v22, v104
	v_pk_mul_f32 v[8:9], v[142:143], v[8:9] op_sel_hi:[0,1]
	v_fmac_f32_e32 v60, v23, v105
	v_pk_fma_f32 v[114:115], v[114:115], v[64:65], v[8:9] op_sel_hi:[1,0,1]
	v_pk_mul_f32 v[0:1], v[142:143], v[0:1] op_sel_hi:[0,1]
	s_waitcnt lgkmcnt(1)
	v_fmac_f32_e32 v60, v4, v114
	v_fmac_f32_e32 v60, v5, v115
	v_pk_mul_f32 v[4:5], v[142:143], v[10:11] op_sel_hi:[0,1]
	v_pk_fma_f32 v[112:113], v[112:113], v[64:65], v[4:5] op_sel_hi:[1,0,1]
	v_pk_fma_f32 v[120:121], v[120:121], v[64:65], v[0:1] op_sel_hi:[1,0,1]
	v_fmac_f32_e32 v60, v6, v112
	v_fmac_f32_e32 v60, v7, v113
	s_waitcnt lgkmcnt(0)
	v_fmac_f32_e32 v60, v12, v120
	v_pk_mul_f32 v[0:1], v[142:143], v[2:3] op_sel_hi:[0,1]
	v_fmac_f32_e32 v60, v13, v121
	v_pk_fma_f32 v[118:119], v[118:119], v[64:65], v[0:1] op_sel_hi:[1,0,1]
	s_nop 0
	v_fmac_f32_e32 v60, v14, v118
	v_fmac_f32_e32 v60, v15, v119
	ds_bpermute_b32 v0, v150, v60
	s_and_saveexec_b64 s[24:25], s[6:7]
	s_cbranch_execz .LBB0_1100
	s_waitcnt lgkmcnt(0)
	v_add_f32_e32 v0, v60, v0
	v_mul_f32_e32 v0, 0x3db504f3, v0
	global_store_dword v[138:139], v0, off
	s_branch .LBB0_1100
